# layer-0 main attention loop (256 units, second inlined copy) now gets the same no-copy + running-max-in-accumulator + trimmed softmax code as layer 1
# speedup vs baseline: 1.0057x; 1.0057x over previous
; #define ATT_LOAD(k0_, k1_, v_, tt) do { const char* kg_ = Kg + (size_t)(tt) * 12288; const char* vg_ = Vg + (size_t)(tt) * 8192; \
;             k0_ = *(const u32x4*)(kg_ + tid_ * 16); if (tid_ < 256) k1_ = *(const u32x4*)(kg_ + (tid_ + 512) * 16); v_ = *(const u32x4*)(vg_ + tid_ * 16); } while (0)
; #define ATT_WRITE(k0_, k1_, v_, bo) do { *(LAS u32x4*)(sm + (bo) + koff0) = k0_; if (tid_ < 256) *(LAS u32x4*)(sm + (bo) + koff1) = k1_; *(LAS u32x4*)(sm + (bo) + voff) = v_; } while (0)
; __device__ __forceinline__ void ph_attn_mfma(unsigned char* lds_, const bf16_t* Q, const bf16_t* Kb, const bf16_t* Vb, bf16_t* Z, int with_ctx, int u0, int ustep) { PH_IDS;
;     ...
;         const bool lat = u < 256; const int bh = lat ? (u >> 3) : (u - 256), qb = lat ? (u & 7) : 8;
;         const int ntile = lat ? 36 : 4;
;         const char* Kg = (const char*)(Kb + (size_t)bh * 2304 * 96); const char* Vg = (const char*)(Vb + (size_t)bh * 2304 * 64);
;         const bf16_t* Qg = Q + ((size_t)bh * 2304 + qb * 256 + wid * 32 + r32) * 96;
;         bf16x8 qf[6];
; #pragma unroll
;         for (int st = 0; st < 6; ++st) qf[st] = *(const bf16x8*)(Qg + 16 * st + 8 * hi);
;         f32x16 o0, o1;
; #pragma unroll
;         for (int r = 0; r < 16; ++r) { o0[r] = 0.f; o1[r] = 0.f; }
;         float mrun = 0.f, lsum = 0.f;
;         f32x16 negm;
; #pragma unroll
;         for (int r = 0; r < 16; ++r) negm[r] = 0.f;
;         u32x4 ka0, ka1, va, kb0, kb1, vb;
;     ...
;         ka1 = (u32x4){0u, 0u, 0u, 0u}; kb1 = ka1;
;         const int npair = ntile >> 1;
;         ATT_LOAD(ka0, ka1, va, 0); ATT_LOAD(kb0, kb1, vb, 1);
;         __syncthreads();
;         ATT_WRITE(ka0, ka1, va, 0); ATT_WRITE(kb0, kb1, vb, BUF_A);
;         if (npair > 1) { ATT_LOAD(ka0, ka1, va, 2); ATT_LOAD(kb0, kb1, vb, 3); }
;         __syncthreads();
;         f32x16 a0, a1, b0, b1;
; #pragma unroll
;         for (int r = 0; r < 16; ++r) { a0[r] = 0.f; a1[r] = 0.f; }
.LBB0_1050:
	s_lshl_b32 s8, s50, 8
	s_ashr_i32 s10, s50, 3
	s_add_i32 s11, s50, 0xffffff00
	s_and_b32 s39, s8, 0x700
	s_cmpk_lt_i32 s50, 0x100
	s_cselect_b64 s[26:27], -1, 0
	s_and_b64 s[8:9], s[26:27], exec
	s_cselect_b32 s56, s39, 0x800
	s_cselect_b32 s38, s10, s11
	v_lshl_add_u64 v[2:3], v[186:187], 0, s[56:57]
	v_mad_i64_i32 v[2:3], s[8:9], s38, v213, v[2:3]
	v_mad_u64_u32 v[4:5], s[8:9], v2, s93, v[190:191]
	v_mov_b32_e32 v2, v5
	v_mad_u64_u32 v[2:3], s[8:9], v3, s93, v[2:3]
	v_mov_b32_e32 v5, v2
	s_mul_i32 s28, s38, 0x6c000
	global_load_dwordx4 v[134:137], v[4:5], off
	global_load_dwordx4 v[138:141], v[4:5], off offset:32
	global_load_dwordx4 v[142:145], v[4:5], off offset:64
	global_load_dwordx4 v[146:149], v[4:5], off offset:96
	global_load_dwordx4 v[150:153], v[4:5], off offset:128
	global_load_dwordx4 v[154:157], v[4:5], off offset:160
	s_mul_hi_i32 s29, s38, 0x6c000
	s_add_u32 s8, s34, s28
	s_addc_u32 s9, s35, s29
	v_lshl_add_u64 v[2:3], s[8:9], 0, v[184:185]
	global_load_dwordx4 v[6:9], v[2:3], off
	v_mov_b32_e32 v132, v130
	v_mov_b32_e32 v133, v130
	v_mov_b32_e32 v131, v130
	v_mov_b64_e32 v[232:233], 0
	v_mov_b64_e32 v[234:235], 0
	v_mov_b64_e32 v[236:237], 0
	v_mov_b64_e32 v[238:239], 0
	v_mov_b64_e32 v[240:241], 0
	v_mov_b64_e32 v[242:243], 0
	v_mov_b64_e32 v[244:245], 0
	v_mov_b64_e32 v[246:247], 0
	s_waitcnt vmcnt(12)
	v_mov_b64_e32 v[160:161], v[132:133]
	v_mov_b64_e32 v[158:159], v[130:131]
	s_and_saveexec_b64 s[10:11], s[4:5]
	s_cbranch_execz .LBB0_1052
	v_lshl_add_u64 v[2:3], s[8:9], 0, v[192:193]
	global_load_dwordx4 v[158:161], v[2:3], off

; __device__ __forceinline__ void attn_pair(const LAS char* sm, int r32, int hi, int vrd, int bufA, int bufB, bool first, const bf16x8 (&qf)[6], fa::f32x16& negm, float& mrun, float& lsum, fa::f32x16& o0, fa::f32x16& o1) {
;     ...
;         if (first || __any(tm > 0.f)) {
;             const float dl = first ? tm : fmaxf(tm, 0.f), alpha = first ? 1.f : __builtin_amdgcn_exp2f(-dl);
;             mrun += dl; lsum *= alpha; carry = dl;
; #pragma unroll
;             for (int r = 0; r < 16; ++r) { a0[r] -= dl; a1[r] -= dl; o0[r] *= alpha; o1[r] *= alpha; negm[r] = -mrun; }
;         }
; __device__ __forceinline__ void att_shift(float tm, bool first, float& mrun, float& lsum, fa::f32x16& o0, fa::f32x16& o1) {
;     if (first || __any(tm > mrun + 8.f)) {
;         tm = fmaxf(tm, __shfl_xor(tm, 32));
;         const float dl = first ? 0.f : fmaxf(tm - mrun, 0.f), alpha = __builtin_amdgcn_exp2f(-dl);
;         mrun = first ? tm : mrun + dl; lsum *= alpha;
; #pragma unroll
;         for (int r = 0; r < 16; ++r) { o0[r] *= alpha; o1[r] *= alpha; }
;     }
; }
.LBB0_1077:
	s_andn2_b64 vcc, exec, s[16:17]
	s_cbranch_vccnz .LBB0_1079
	v_and_b32_e32 v35, 64, v1
	v_xor_b32_e32 v34, 32, v1
	v_add_u32_e32 v35, 64, v35
	v_cmp_lt_i32_e32 vcc, v34, v35
	v_max_f32_e32 v35, v201, v201
	s_nop 0
	v_cndmask_b32_e32 v34, v1, v34, vcc
	v_lshlrev_b32_e32 v34, 2, v34
	ds_bpermute_b32 v34, v34, v201
	s_waitcnt lgkmcnt(0)
	v_max_f32_e32 v34, v34, v34
	v_max_f32_e32 v35, v35, v34
	v_mov_b32_e32 v34, v35
	v_max_f32_e32 v36, 0, v34
	v_cndmask_b32_e64 v248, v36, v35, s[14:15]
	v_cndmask_b32_e64 v34, -v36, v212, s[14:15]
	v_exp_f32_e32 v34, v34
	v_add_f32_e32 v36, v131, v36
	v_cndmask_b32_e64 v131, v36, v35, s[14:15]
	v_mul_f32_e32 v98, v98, v34
	v_pk_mul_f32 v[96:97], v[96:97], v[34:35] op_sel_hi:[1,0]
	v_pk_mul_f32 v[94:95], v[94:95], v[34:35] op_sel_hi:[1,0]
	v_pk_mul_f32 v[92:93], v[92:93], v[34:35] op_sel_hi:[1,0]
	v_pk_mul_f32 v[90:91], v[90:91], v[34:35] op_sel_hi:[1,0]
	v_pk_mul_f32 v[88:89], v[88:89], v[34:35] op_sel_hi:[1,0]
	v_pk_mul_f32 v[86:87], v[86:87], v[34:35] op_sel_hi:[1,0]
	v_pk_mul_f32 v[84:85], v[84:85], v[34:35] op_sel_hi:[1,0]
	v_pk_mul_f32 v[82:83], v[82:83], v[34:35] op_sel_hi:[1,0]
	v_pk_mul_f32 v[80:81], v[80:81], v[34:35] op_sel_hi:[1,0]
	v_pk_mul_f32 v[78:79], v[78:79], v[34:35] op_sel_hi:[1,0]
	v_pk_mul_f32 v[76:77], v[76:77], v[34:35] op_sel_hi:[1,0]
	v_pk_mul_f32 v[74:75], v[74:75], v[34:35] op_sel_hi:[1,0]
	v_pk_mul_f32 v[72:73], v[72:73], v[34:35] op_sel_hi:[1,0]
	v_pk_mul_f32 v[70:71], v[70:71], v[34:35] op_sel_hi:[1,0]
	v_pk_mul_f32 v[68:69], v[68:69], v[34:35] op_sel_hi:[1,0]
	v_pk_mul_f32 v[66:67], v[66:67], v[34:35] op_sel_hi:[1,0]
	v_sub_f32_e32 v2, v2, v248
	v_sub_f32_e32 v3, v3, v248
	v_sub_f32_e32 v4, v4, v248
	v_sub_f32_e32 v5, v5, v248
	v_sub_f32_e32 v6, v6, v248
	v_sub_f32_e32 v7, v7, v248
	v_sub_f32_e32 v8, v8, v248
	v_sub_f32_e32 v9, v9, v248
	v_sub_f32_e32 v10, v10, v248
	v_sub_f32_e32 v11, v11, v248
	v_sub_f32_e32 v12, v12, v248
	v_sub_f32_e32 v13, v13, v248
	v_sub_f32_e32 v14, v14, v248
	v_sub_f32_e32 v15, v15, v248
	v_sub_f32_e32 v16, v16, v248
	v_sub_f32_e32 v17, v17, v248
	v_sub_f32_e32 v18, v18, v248
	v_sub_f32_e32 v19, v19, v248
	v_sub_f32_e32 v20, v20, v248
	v_sub_f32_e32 v21, v21, v248
	v_sub_f32_e32 v22, v22, v248
	v_sub_f32_e32 v23, v23, v248
	v_sub_f32_e32 v24, v24, v248
	v_sub_f32_e32 v25, v25, v248
	v_sub_f32_e32 v26, v26, v248
	v_sub_f32_e32 v27, v27, v248
	v_sub_f32_e32 v28, v28, v248
	v_sub_f32_e32 v29, v29, v248
	v_sub_f32_e32 v30, v30, v248
	v_sub_f32_e32 v31, v31, v248
	v_sub_f32_e32 v32, v32, v248
	v_sub_f32_e32 v33, v33, v248
	v_sub_f32_e32 v232, v232, v248
	v_sub_f32_e32 v233, v233, v248
	v_sub_f32_e32 v234, v234, v248
	v_sub_f32_e32 v235, v235, v248
	v_sub_f32_e32 v236, v236, v248
	v_sub_f32_e32 v237, v237, v248
	v_sub_f32_e32 v238, v238, v248
	v_sub_f32_e32 v239, v239, v248
	v_sub_f32_e32 v240, v240, v248
	v_sub_f32_e32 v241, v241, v248
	v_sub_f32_e32 v242, v242, v248
	v_sub_f32_e32 v243, v243, v248
	v_sub_f32_e32 v244, v244, v248
	v_sub_f32_e32 v245, v245, v248
	v_sub_f32_e32 v246, v246, v248
	v_sub_f32_e32 v247, v247, v248

; #define LAS __attribute__((address_space(3)))
; __device__ __forceinline__ void att_qk_exp(const LAS char* kb, const bf16x8 (&qf)[6], float nm, fa::f32x16& n0, fa::f32x16& n1, fa::f32x16& p0, fa::f32x16& p1, float& lsum, bf16x8 (&pf)[4]) {
;     const fa::f32x16 zero = {0.f, 0.f, 0.f, 0.f, 0.f, 0.f, 0.f, 0.f, 0.f, 0.f, 0.f, 0.f, 0.f, 0.f, 0.f, 0.f};
;     bf16x8 kc0 = *(const LAS bf16x8*)kb, kc1 = *(const LAS bf16x8*)(kb + 32 * fa::KP_A);
;     float ps = 0.f, ps2 = 0.f;
; #pragma unroll
;     for (int st = 0; st < 6; ++st) {
;         bf16x8 kn0 = kc0, kn1 = kc1;
;         if (st < 5) { kn0 = *(const LAS bf16x8*)(kb + 32 * (st + 1)); kn1 = *(const LAS bf16x8*)(kb + 32 * fa::KP_A + 32 * (st + 1)); }
;         n0 = __builtin_amdgcn_mfma_f32_32x32x16_bf16(kc0, qf[st], st == 0 ? zero : n0, 0, 0, 0);
;         n1 = __builtin_amdgcn_mfma_f32_32x32x16_bf16(kc1, qf[st], st == 0 ? zero : n1, 0, 0, 0);
;         constexpr int lo[7] = {0, 2, 6, 8, 10, 14, 16};
; #pragma unroll
;         for (int r = lo[st]; r < lo[st + 1]; ++r) {
;             p0[r] = __builtin_amdgcn_exp2f(vadd1(p0[r], nm)); p1[r] = __builtin_amdgcn_exp2f(vadd1(p1[r], nm));
;             ps += p0[r]; ps += p1[r]; }
;         kc0 = kn0; kc1 = kn1;
;         __builtin_amdgcn_sched_barrier(0);
;     }
;     lsum += ps + ps2;
;     pf[0] = fa::pack_p(p0, 0); pf[1] = fa::pack_p(p0, 8); pf[2] = fa::pack_p(p1, 0); pf[3] = fa::pack_p(p1, 8);
; }
; __device__ __forceinline__ void att_exp_pack(fa::f32x16& p0, fa::f32x16& p1, float nm, float& lsum, bf16x8 (&pf)[4]) {
;     float ps = 0.f, ps2 = 0.f;
; #pragma unroll
;     for (int r = 0; r < 16; ++r) { p0[r] = __builtin_amdgcn_exp2f(vadd1(p0[r], nm)); p1[r] = __builtin_amdgcn_exp2f(vadd1(p1[r], nm)); ps += p0[r]; ps += p1[r]; }
;     lsum += ps + ps2;
;     pf[0] = fa::pack_p(p0, 0); pf[1] = fa::pack_p(p0, 8); pf[2] = fa::pack_p(p1, 0); pf[3] = fa::pack_p(p1, 8);
; }
; __device__ __forceinline__ float att_pv_max(fa::f32x16& o0, fa::f32x16& o1, const LAS char* vb, const bf16x8 (&pf)[4], const fa::f32x16& n0, const fa::f32x16& n1) {
;     using namespace fa;
;     float ta = n0[0], tb = n1[0];
;     s16x4 a0 = vtr(vb), a1 = vtr(vb + 512), b0 = vtr(vb + 4096), b1 = vtr(vb + 4096 + 512);
; #pragma unroll
;     for (int ks = 0; ks < 4; ++ks) {
;         s16x4 na0 = a0, na1 = a1, nb0 = b0, nb1 = b1;
.LBB0_1083:
	s_andn2_b64 vcc, exec, s[8:9]
	s_cbranch_vccnz .LBB0_1085
	v_add_u32_e32 v98, s20, v218
	ds_read_b128 v[2:5], v98
	ds_read_b128 v[18:21], v98 offset:6656
	ds_read_b128 v[114:117], v98 offset:32
	ds_read_b128 v[118:121], v98 offset:6688
	v_exp_f32_e32 v99, v34
	v_exp_f32_e32 v100, v50
	s_waitcnt lgkmcnt(3)
	v_mfma_f32_32x32x16_bf16 v[2:17], v[2:5], v[134:137], v[232:247]
	v_exp_f32_e32 v101, v35
	v_exp_f32_e32 v102, v51
	s_waitcnt lgkmcnt(2)
	v_mfma_f32_32x32x16_bf16 v[18:33], v[18:21], v[134:137], v[232:247]
	s_waitcnt lgkmcnt(1)
	v_mfma_f32_32x32x16_bf16 v[2:17], v[114:117], v[138:141], v[2:17]
	v_exp_f32_e32 v103, v36
	ds_read_b128 v[122:125], v98 offset:64
	ds_read_b128 v[126:129], v98 offset:6720
	v_exp_f32_e32 v104, v52
	v_exp_f32_e32 v114, v37
	s_waitcnt lgkmcnt(2)
	v_mfma_f32_32x32x16_bf16 v[18:33], v[118:121], v[138:141], v[18:33]
	v_exp_f32_e32 v115, v53
	v_exp_f32_e32 v116, v38
	v_exp_f32_e32 v117, v54
	v_exp_f32_e32 v105, v39
	v_exp_f32_e32 v106, v55
	s_waitcnt lgkmcnt(1)
	v_mfma_f32_32x32x16_bf16 v[2:17], v[122:125], v[142:145], v[2:17]
	ds_read_b128 v[34:37], v98 offset:96
	ds_read_b128 v[50:53], v98 offset:6752
	v_exp_f32_e32 v118, v40
	v_exp_f32_e32 v119, v56
	s_waitcnt lgkmcnt(2)
	v_mfma_f32_32x32x16_bf16 v[18:33], v[126:129], v[142:145], v[18:33]
	v_exp_f32_e32 v120, v41
	v_exp_f32_e32 v121, v57
	s_waitcnt lgkmcnt(1)
	v_mfma_f32_32x32x16_bf16 v[2:17], v[34:37], v[146:149], v[2:17]
	ds_read_b128 v[38:41], v98 offset:128
	ds_read_b128 v[54:57], v98 offset:6784
	v_exp_f32_e32 v42, v42
	v_exp_f32_e32 v58, v58
	s_waitcnt lgkmcnt(2)
	v_mfma_f32_32x32x16_bf16 v[18:33], v[50:53], v[146:149], v[18:33]
	v_exp_f32_e32 v43, v43
	v_exp_f32_e32 v59, v59
	s_waitcnt lgkmcnt(1)
	v_mfma_f32_32x32x16_bf16 v[2:17], v[38:41], v[150:153], v[2:17]
	ds_read_b128 v[34:37], v98 offset:160
	ds_read_b128 v[50:53], v98 offset:6816
	v_exp_f32_e32 v39, v45
	s_waitcnt lgkmcnt(2)
	v_mfma_f32_32x32x16_bf16 v[18:33], v[54:57], v[150:153], v[18:33]
	v_exp_f32_e32 v61, v61
	v_exp_f32_e32 v44, v44
	v_exp_f32_e32 v40, v46
	v_exp_f32_e32 v60, v60
	v_exp_f32_e32 v62, v62
	v_exp_f32_e32 v41, v47
	v_exp_f32_e32 v63, v63
	s_waitcnt lgkmcnt(1)
	v_mfma_f32_32x32x16_bf16 v[2:17], v[34:37], v[154:157], v[2:17]
	v_exp_f32_e32 v45, v48
	v_exp_f32_e32 v54, v64
	v_mov_b32_e32 v38, v49
	v_exp_f32_e32 v49, v65
	v_add_f32_e32 v34, v100, v99
	v_add_f32_e32 v34, v34, v101
	v_add_f32_e32 v34, v102, v34
	v_add_f32_e32 v34, v34, v103
	v_add_f32_e32 v34, v104, v34
	v_add_f32_e32 v34, v34, v114
	v_add_f32_e32 v34, v115, v34
	v_add_f32_e32 v34, v34, v116
	v_add_f32_e32 v34, v117, v34
	v_add_f32_e32 v34, v34, v105
	v_add_f32_e32 v34, v106, v34
	v_add_f32_e32 v34, v34, v118
	v_add_f32_e32 v34, v119, v34
	v_add_f32_e32 v34, v34, v120
	v_add_f32_e32 v34, v121, v34
	v_add_f32_e32 v34, v34, v42
	v_add_f32_e32 v34, v58, v34
	v_add_f32_e32 v34, v34, v43
	v_add_f32_e32 v34, v59, v34
	v_add_f32_e32 v34, v34, v44
	v_add_f32_e32 v34, v60, v34
	v_add_f32_e32 v34, v34, v39
	v_add_f32_e32 v34, v61, v34
	s_waitcnt lgkmcnt(0)
	v_mfma_f32_32x32x16_bf16 v[18:33], v[50:53], v[154:157], v[18:33]
	v_add_f32_e32 v34, v34, v40
	v_add_f32_e32 v34, v62, v34
	v_exp_f32_e32 v46, v38
	v_add_f32_e32 v34, v34, v41
	v_add_f32_e32 v34, v63, v34
	v_add_f32_e32 v34, v34, v45
	v_add_f32_e32 v34, v54, v34
	v_add_f32_e32 v34, v34, v46
	v_add_f32_e32 v223, v49, v34
	v_cvt_pk_bf16_f32 v34, v99, v101
	v_cvt_pk_bf16_f32 v35, v103, v114
	v_cvt_pk_bf16_f32 v36, v116, v105
	v_cvt_pk_bf16_f32 v37, v118, v120
	v_cvt_pk_bf16_f32 v38, v42, v43
	v_cvt_pk_bf16_f32 v39, v44, v39
	v_cvt_pk_bf16_f32 v40, v40, v41
	v_cvt_pk_bf16_f32 v41, v45, v46
	v_cvt_pk_bf16_f32 v42, v100, v102
	v_cvt_pk_bf16_f32 v43, v104, v115
	v_cvt_pk_bf16_f32 v44, v117, v106
	v_cvt_pk_bf16_f32 v45, v119, v121
	v_cvt_pk_bf16_f32 v46, v58, v59
	v_cvt_pk_bf16_f32 v47, v60, v61
	v_cvt_pk_bf16_f32 v48, v62, v63
	v_cvt_pk_bf16_f32 v49, v54, v49
	ds_read_b64_tr_b16 v[50:51], v221 offset:34816
	ds_read_b64_tr_b16 v[52:53], v221 offset:35328
	ds_read_b64_tr_b16 v[54:55], v221 offset:35840
	ds_read_b64_tr_b16 v[56:57], v221 offset:36352
	s_waitcnt lgkmcnt(2)
	v_mfma_f32_32x32x16_bf16 v[82:97], v[50:53], v[34:37], v[82:97]
	ds_read_b64_tr_b16 v[50:51], v221 offset:38912
	ds_read_b64_tr_b16 v[52:53], v221 offset:39424
	ds_read_b64_tr_b16 v[58:59], v221 offset:39936
	ds_read_b64_tr_b16 v[60:61], v221 offset:40448
	s_waitcnt lgkmcnt(2)
	v_mfma_f32_32x32x16_bf16 v[66:81], v[50:53], v[34:37], v[66:81]
	ds_read_b64_tr_b16 v[34:35], v221 offset:36864
	ds_read_b64_tr_b16 v[36:37], v221 offset:37376
	ds_read_b64_tr_b16 v[50:51], v221 offset:40960
	ds_read_b64_tr_b16 v[52:53], v221 offset:41472
	v_mfma_f32_32x32x16_bf16 v[82:97], v[54:57], v[38:41], v[82:97]
	s_waitcnt lgkmcnt(4)
	v_mfma_f32_32x32x16_bf16 v[66:81], v[58:61], v[38:41], v[66:81]
	s_waitcnt lgkmcnt(2)
	v_mfma_f32_32x32x16_bf16 v[82:97], v[34:37], v[42:45], v[82:97]
	ds_read_b64_tr_b16 v[34:35], v221 offset:37888
	ds_read_b64_tr_b16 v[36:37], v221 offset:38400
	ds_read_b64_tr_b16 v[38:39], v221 offset:41984
	ds_read_b64_tr_b16 v[40:41], v221 offset:42496
	s_waitcnt lgkmcnt(4)
	v_mfma_f32_32x32x16_bf16 v[66:81], v[50:53], v[42:45], v[66:81]
	v_max_f32_e32 v42, v19, v19
	v_max_f32_e32 v43, v18, v18
	v_max_f32_e32 v42, v43, v42
	v_max3_f32 v42, v42, v20, v21
	s_waitcnt lgkmcnt(2)
	v_mfma_f32_32x32x16_bf16 v[82:97], v[34:37], v[46:49], v[82:97]
	v_max3_f32 v35, v2, v3, v4
	v_max3_f32 v42, v42, v22, v23
	v_max3_f32 v35, v35, v5, v6
	v_max3_f32 v42, v42, v24, v25
	v_max3_f32 v35, v35, v7, v8
	v_max3_f32 v34, v42, v26, v27
	v_max3_f32 v35, v35, v9, v10
	v_max3_f32 v34, v34, v28, v29
	v_max3_f32 v35, v35, v11, v12
	v_max3_f32 v35, v35, v13, v14
	v_max3_f32 v34, v34, v30, v31
	s_waitcnt lgkmcnt(0)
	v_mfma_f32_32x32x16_bf16 v[66:81], v[38:41], v[46:49], v[66:81]
	v_max3_f32 v35, v35, v15, v16
	v_max3_f32 v34, v34, v32, v33
	v_max3_f32 v201, v35, v17, v34
